# same as previous plus grid-size guards: helper partition and adaLN remap only used when gridDim is 256, otherwise full-range fallback
# baseline (speedup 1.0000x reference)
.LBB0_29:
	s_mov_b64 s[54:55], 0
	s_load_dword s12, s[90:91], 0xd8
	v_mbcnt_lo_u32_b32 v0, -1, 0
	v_mbcnt_hi_u32_b32 v0, -1, v0
	s_mov_b32 s0, s88
	v_or_b32_e32 v76, s94, v0
	s_waitcnt lgkmcnt(0)
	s_mov_b32 s1, s12
	v_mov_b32_e32 v1, v76
	s_mov_b32 s0, s88
	v_ashrrev_i32_e32 v2, 6, v1
	s_add_u32 s56, s86, s54
	s_movk_i32 s1, 0x600
	v_lshl_add_u32 v38, s0, 3, v2
	s_mov_b64 s[4:5], 0
	s_addc_u32 s57, s87, s55
	s_cmp_lg_u32 s12, 256
	s_cbranch_scc1 .Lada_keepmap
	s_mul_i32 s98, s88, 6
	v_add_u32_e32 v38, s98, v2
	v_mov_b32_e32 v3, 0x600
	v_cmp_gt_u32_e32 vcc, 6, v2
	s_nop 1
	v_cndmask_b32_e32 v38, v3, v38, vcc
.Lada_keepmap:
	s_mov_b32 s0, s12
	v_cmp_gt_i32_e32 vcc, s1, v38
	s_and_saveexec_b64 s[6:7], vcc
	s_cbranch_execz .LBB0_36
	v_bfe_u32 v6, v1, 2, 4
	v_lshlrev_b32_e32 v1, 2, v1
	v_and_b32_e32 v39, 12, v1
	v_and_b32_e32 v1, 64, v0
	v_add_u32_e32 v1, 64, v1
	v_xor_b32_e32 v4, 4, v0
	v_cmp_lt_i32_e32 vcc, v4, v1
	s_load_dwordx16 s[16:31], s[90:91], 0x0
	s_lshl_b64 s[8:9], s[54:55], 2
	v_cndmask_b32_e32 v4, v0, v4, vcc
	v_lshlrev_b32_e32 v40, 2, v4
	v_xor_b32_e32 v4, 8, v0
	v_cmp_lt_i32_e32 vcc, v4, v1
	s_waitcnt lgkmcnt(0)
	v_mov_b32_e32 v2, s24
	v_mov_b32_e32 v3, s25
	v_cndmask_b32_e32 v4, v0, v4, vcc
	v_lshlrev_b32_e32 v41, 2, v4
	v_xor_b32_e32 v4, 16, v0
	v_cmp_lt_i32_e32 vcc, v4, v1
	s_mov_b32 s1, 0xc000
	s_add_u32 s10, s26, s8
	v_cndmask_b32_e32 v4, v0, v4, vcc
	v_lshlrev_b32_e32 v42, 2, v4
	v_xor_b32_e32 v4, 32, v0
	v_cmp_lt_i32_e32 vcc, v4, v1
	v_cmp_eq_u32_e64 s[2:3], 0, v6
	v_mov_b32_e32 v7, 0
	v_cndmask_b32_e32 v0, v0, v4, vcc
	v_mad_u64_u32 v[4:5], s[14:15], v6, s1, v[2:3]
	v_lshlrev_b32_e32 v6, 2, v6
	s_addc_u32 s11, s27, s9
	s_lshl_b32 s0, s0, 3
	v_lshlrev_b32_e32 v43, 2, v0
	v_lshl_add_u64 v[8:9], s[18:19], 0, v[6:7]
	v_lshl_add_u64 v[10:11], s[22:23], 0, v[6:7]
	s_mov_b32 s13, 0x2aaaaaab
	s_mov_b32 s14, 0x6000000
	s_movk_i32 s15, 0x2000
	s_mov_b32 s16, 0xc0000
	s_mov_b32 s17, 0x180000
	s_mov_b32 s20, 0x240000
	s_mov_b32 s21, 0x300000
	s_mov_b32 s26, 0x3c0000
	s_mov_b32 s27, 0x480000
	s_mov_b32 s28, 0x540000
	s_mov_b64 s[18:19], 0x600000
	s_mov_b64 s[22:23], 0x200
	s_movk_i32 s29, 0x5ff
	s_branch .LBB0_32

.LBB0_115:
	s_or_b64 exec, exec, s[2:3]
	s_abs_i32 s15, s12
	v_cvt_f32_u32_e32 v2, s15
	v_lshlrev_b32_e32 v0, 2, v76
	v_and_b32_e32 v82, 60, v0
	s_sub_i32 s2, 0, s15
	v_rcp_iflag_f32_e32 v0, v2
	s_mov_b32 s13, s88
	s_add_i32 s14, s13, s12
	v_mul_f32_e32 v0, 0x4f7ffffe, v0
	v_cvt_u32_f32_e32 v0, v0
	s_abs_i32 s1, s14
	s_ashr_i32 s0, s14, 31
	v_ashrrev_i32_e32 v78, 3, v76
	v_readfirstlane_b32 s16, v0
	s_mul_i32 s2, s2, s16
	s_mul_hi_u32 s2, s16, s2
	s_add_i32 s16, s16, s2
	s_mul_hi_u32 s2, s1, s16
	s_mul_i32 s2, s2, s15
	s_sub_i32 s1, s1, s2
	s_sub_i32 s2, s1, s15
	s_cmp_ge_u32 s1, s15
	s_cselect_b32 s1, s2, s1
	s_sub_i32 s2, s1, s15
	s_cmp_ge_u32 s1, s15
	s_cselect_b32 s1, s2, s1
	s_xor_b32 s1, s1, s0
	v_lshlrev_b32_e32 v2, 3, v76
	s_sub_i32 s17, s1, s0
	v_ashrrev_i32_e32 v77, 4, v76
	v_mov_b32_e32 v1, 0
	v_lshl_add_u32 v79, v82, 2, 0
	v_and_b32_e32 v80, 56, v2
	s_cmpk_lt_i32 s17, 0x480
	v_lshl_add_u32 v81, v78, 2, 0
	s_load_dword s59, s[90:91], 0xd8
	v_mbcnt_lo_u32_b32 v100, -1, 0
	v_mbcnt_hi_u32_b32 v100, -1, v100
	s_lshr_b32 s69, s94, 6
	s_lshl_b32 s82, s69, 10
	s_lshl_b32 s83, s69, 1
	s_lshr_b32 s98, s69, 2
	v_lshrrev_b32_e32 v101, 5, v100
	v_and_b32_e32 v113, 31, v100
	s_add_i32 s70, s83, 0
	v_add_u32_e32 v102, s70, v101
	s_add_i32 s70, s98, 0
	v_xor_b32_e32 v106, s70, v113
	v_lshlrev_b32_e32 v106, 4, v106
	s_add_i32 s70, s83, 16
	v_add_u32_e32 v103, s70, v101
	s_add_i32 s70, s98, 2
	v_xor_b32_e32 v107, s70, v113
	v_lshlrev_b32_e32 v107, 4, v107
	s_add_i32 s70, s83, 32
	v_add_u32_e32 v104, s70, v101
	s_add_i32 s70, s98, 4
	v_xor_b32_e32 v108, s70, v113
	v_lshlrev_b32_e32 v108, 4, v108
	s_add_i32 s70, s83, 48
	v_add_u32_e32 v105, s70, v101
	s_add_i32 s70, s98, 6
	v_xor_b32_e32 v109, s70, v113
	v_lshlrev_b32_e32 v109, 4, v109
	s_lshr_b32 s70, s94, 3
	v_lshrrev_b32_e32 v112, 3, v100
	v_add_u32_e32 v112, s70, v112
	v_and_b32_e32 v101, 7, v100
	v_lshlrev_b32_e32 v111, 4, v101
	v_lshrrev_b32_e32 v113, 2, v112
	v_xor_b32_e32 v113, v113, v101
	v_lshlrev_b32_e32 v113, 4, v113
	v_lshl_add_u32 v110, v101, 12, v113
	v_and_b32_e32 v113, 3, v112
	v_lshl_add_u32 v110, v113, 2, v110
	s_waitcnt lgkmcnt(0)
	s_add_u32 s61, s88, 0
	s_mov_b32 s101, 5280
	s_cmp_eq_u32 s59, 256
	s_cbranch_scc1 .Lwp0_gridok
	s_mov_b32 s61, s88
	s_mov_b32 s101, 7520
.Lwp0_gridok:
	s_mov_b32 s60, s61
	s_mov_b32 s58, -2

.LBB0_290:
	s_barrier
	s_cmp_lt_u32 s88, 200
	s_cbranch_scc1 .Lwph2_skip
	s_load_dword s59, s[90:91], 0xd8
	v_mbcnt_lo_u32_b32 v100, -1, 0
	v_mbcnt_hi_u32_b32 v100, -1, v100
	s_lshr_b32 s69, s94, 6
	s_lshl_b32 s82, s69, 10
	s_lshl_b32 s83, s69, 1
	s_lshr_b32 s98, s69, 2
	v_lshrrev_b32_e32 v101, 5, v100
	v_and_b32_e32 v113, 31, v100
	s_add_i32 s70, s83, 0
	v_add_u32_e32 v102, s70, v101
	s_add_i32 s70, s98, 0
	v_xor_b32_e32 v106, s70, v113
	v_lshlrev_b32_e32 v106, 4, v106
	s_add_i32 s70, s83, 16
	v_add_u32_e32 v103, s70, v101
	s_add_i32 s70, s98, 2
	v_xor_b32_e32 v107, s70, v113
	v_lshlrev_b32_e32 v107, 4, v107
	s_add_i32 s70, s83, 32
	v_add_u32_e32 v104, s70, v101
	s_add_i32 s70, s98, 4
	v_xor_b32_e32 v108, s70, v113
	v_lshlrev_b32_e32 v108, 4, v108
	s_add_i32 s70, s83, 48
	v_add_u32_e32 v105, s70, v101
	s_add_i32 s70, s98, 6
	v_xor_b32_e32 v109, s70, v113
	v_lshlrev_b32_e32 v109, 4, v109
	s_lshr_b32 s70, s94, 3
	v_lshrrev_b32_e32 v112, 3, v100
	v_add_u32_e32 v112, s70, v112
	v_and_b32_e32 v101, 7, v100
	v_lshlrev_b32_e32 v111, 4, v101
	v_lshrrev_b32_e32 v113, 2, v112
	v_xor_b32_e32 v113, v113, v101
	v_lshlrev_b32_e32 v113, 4, v113
	v_lshl_add_u32 v110, v101, 12, v113
	v_and_b32_e32 v113, 3, v112
	v_lshl_add_u32 v110, v113, 2, v110
	s_waitcnt lgkmcnt(0)
	s_cmp_lg_u32 s59, 256
	s_cbranch_scc1 .Lwph2_end
	s_sub_u32 s61, s88, 200
	s_add_u32 s61, s61, 5280
	s_mov_b32 s59, 56
	s_mov_b32 s101, 7520
	s_mov_b32 s60, s61
	s_mov_b32 s58, -2

.LBB0_586:
	v_readlane_b32 s90, v245, 61
	v_readlane_b32 s92, v245, 59
	v_readlane_b32 s96, v245, 56
	v_readlane_b32 s16, v245, 53
	v_readlane_b32 s88, v245, 63
	v_readlane_b32 s91, v245, 62
	v_readlane_b32 s93, v245, 60
	v_readlane_b32 s94, v245, 58
	v_readlane_b32 s97, v245, 57
	v_readlane_b32 s95, v245, 55
	v_readlane_b32 s17, v245, 54
	s_barrier
	s_cmp_lt_u32 s88, 64
	s_cbranch_scc1 .Lwph6_skip
	s_load_dword s59, s[90:91], 0xd8
	v_mbcnt_lo_u32_b32 v100, -1, 0
	v_mbcnt_hi_u32_b32 v100, -1, v100
	s_lshr_b32 s69, s94, 6
	s_lshl_b32 s82, s69, 10
	s_lshl_b32 s83, s69, 1
	s_lshr_b32 s98, s69, 2
	v_lshrrev_b32_e32 v101, 5, v100
	v_and_b32_e32 v113, 31, v100
	s_add_i32 s70, s83, 0
	v_add_u32_e32 v102, s70, v101
	s_add_i32 s70, s98, 0
	v_xor_b32_e32 v106, s70, v113
	v_lshlrev_b32_e32 v106, 4, v106
	s_add_i32 s70, s83, 16
	v_add_u32_e32 v103, s70, v101
	s_add_i32 s70, s98, 2
	v_xor_b32_e32 v107, s70, v113
	v_lshlrev_b32_e32 v107, 4, v107
	s_add_i32 s70, s83, 32
	v_add_u32_e32 v104, s70, v101
	s_add_i32 s70, s98, 4
	v_xor_b32_e32 v108, s70, v113
	v_lshlrev_b32_e32 v108, 4, v108
	s_add_i32 s70, s83, 48
	v_add_u32_e32 v105, s70, v101
	s_add_i32 s70, s98, 6
	v_xor_b32_e32 v109, s70, v113
	v_lshlrev_b32_e32 v109, 4, v109
	s_lshr_b32 s70, s94, 3
	v_lshrrev_b32_e32 v112, 3, v100
	v_add_u32_e32 v112, s70, v112
	v_and_b32_e32 v101, 7, v100
	v_lshlrev_b32_e32 v111, 4, v101
	v_lshrrev_b32_e32 v113, 2, v112
	v_xor_b32_e32 v113, v113, v101
	v_lshlrev_b32_e32 v113, 4, v113
	v_lshl_add_u32 v110, v101, 12, v113
	v_and_b32_e32 v113, 3, v112
	v_lshl_add_u32 v110, v113, 2, v110
	s_waitcnt lgkmcnt(0)
	s_cmp_lg_u32 s59, 256
	s_cbranch_scc1 .Lwph6_end
	s_sub_u32 s61, s88, 64
	s_add_u32 s61, s61, 0
	s_mov_b32 s59, 192
	s_mov_b32 s101, 768
	s_mov_b32 s60, s61
	s_mov_b32 s58, -2

.LBB0_710:
	s_barrier
	s_cmp_lt_u32 s88, 216
	s_cbranch_scc1 .Lwph9_skip
	s_load_dword s59, s[90:91], 0xd8
	v_mbcnt_lo_u32_b32 v100, -1, 0
	v_mbcnt_hi_u32_b32 v100, -1, v100
	s_lshr_b32 s69, s94, 6
	s_lshl_b32 s82, s69, 10
	s_lshl_b32 s83, s69, 1
	s_lshr_b32 s98, s69, 2
	v_lshrrev_b32_e32 v101, 5, v100
	v_and_b32_e32 v113, 31, v100
	s_add_i32 s70, s83, 0
	v_add_u32_e32 v102, s70, v101
	s_add_i32 s70, s98, 0
	v_xor_b32_e32 v106, s70, v113
	v_lshlrev_b32_e32 v106, 4, v106
	s_add_i32 s70, s83, 16
	v_add_u32_e32 v103, s70, v101
	s_add_i32 s70, s98, 2
	v_xor_b32_e32 v107, s70, v113
	v_lshlrev_b32_e32 v107, 4, v107
	s_add_i32 s70, s83, 32
	v_add_u32_e32 v104, s70, v101
	s_add_i32 s70, s98, 4
	v_xor_b32_e32 v108, s70, v113
	v_lshlrev_b32_e32 v108, 4, v108
	s_add_i32 s70, s83, 48
	v_add_u32_e32 v105, s70, v101
	s_add_i32 s70, s98, 6
	v_xor_b32_e32 v109, s70, v113
	v_lshlrev_b32_e32 v109, 4, v109
	s_lshr_b32 s70, s94, 3
	v_lshrrev_b32_e32 v112, 3, v100
	v_add_u32_e32 v112, s70, v112
	v_and_b32_e32 v101, 7, v100
	v_lshlrev_b32_e32 v111, 4, v101
	v_lshrrev_b32_e32 v113, 2, v112
	v_xor_b32_e32 v113, v113, v101
	v_lshlrev_b32_e32 v113, 4, v113
	v_lshl_add_u32 v110, v101, 12, v113
	v_and_b32_e32 v113, 3, v112
	v_lshl_add_u32 v110, v113, 2, v110
	s_waitcnt lgkmcnt(0)
	s_cmp_lg_u32 s59, 256
	s_cbranch_scc1 .Lwph9_end
	s_sub_u32 s61, s88, 216
	s_add_u32 s61, s61, 768
	s_mov_b32 s59, 40
	s_mov_b32 s101, 2368
	s_mov_b32 s60, s61
	s_mov_b32 s58, -2

.LBB0_771:
	s_barrier
	s_cmp_lt_u32 s88, 176
	s_cbranch_scc1 .Lwph10_skip
	s_load_dword s59, s[90:91], 0xd8
	v_mbcnt_lo_u32_b32 v100, -1, 0
	v_mbcnt_hi_u32_b32 v100, -1, v100
	s_lshr_b32 s69, s94, 6
	s_lshl_b32 s82, s69, 10
	s_lshl_b32 s83, s69, 1
	s_lshr_b32 s98, s69, 2
	v_lshrrev_b32_e32 v101, 5, v100
	v_and_b32_e32 v113, 31, v100
	s_add_i32 s70, s83, 0
	v_add_u32_e32 v102, s70, v101
	s_add_i32 s70, s98, 0
	v_xor_b32_e32 v106, s70, v113
	v_lshlrev_b32_e32 v106, 4, v106
	s_add_i32 s70, s83, 16
	v_add_u32_e32 v103, s70, v101
	s_add_i32 s70, s98, 2
	v_xor_b32_e32 v107, s70, v113
	v_lshlrev_b32_e32 v107, 4, v107
	s_add_i32 s70, s83, 32
	v_add_u32_e32 v104, s70, v101
	s_add_i32 s70, s98, 4
	v_xor_b32_e32 v108, s70, v113
	v_lshlrev_b32_e32 v108, 4, v108
	s_add_i32 s70, s83, 48
	v_add_u32_e32 v105, s70, v101
	s_add_i32 s70, s98, 6
	v_xor_b32_e32 v109, s70, v113
	v_lshlrev_b32_e32 v109, 4, v109
	s_lshr_b32 s70, s94, 3
	v_lshrrev_b32_e32 v112, 3, v100
	v_add_u32_e32 v112, s70, v112
	v_and_b32_e32 v101, 7, v100
	v_lshlrev_b32_e32 v111, 4, v101
	v_lshrrev_b32_e32 v113, 2, v112
	v_xor_b32_e32 v113, v113, v101
	v_lshlrev_b32_e32 v113, 4, v113
	v_lshl_add_u32 v110, v101, 12, v113
	v_and_b32_e32 v113, 3, v112
	v_lshl_add_u32 v110, v113, 2, v110
	s_waitcnt lgkmcnt(0)
	s_cmp_lg_u32 s59, 256
	s_cbranch_scc1 .Lwph10_end
	s_sub_u32 s61, s88, 176
	s_add_u32 s61, s61, 2368
	s_mov_b32 s59, 80
	s_mov_b32 s101, 3008
	s_mov_b32 s60, s61
	s_mov_b32 s58, -2

.LBB0_784:
	s_mov_b64 s[4:5], 0
	s_load_dword s12, s[90:91], 0xd8
	v_mbcnt_lo_u32_b32 v0, -1, 0
	v_mbcnt_hi_u32_b32 v77, -1, v0
	v_or_b32_e32 v76, s94, v77
	s_mov_b32 s0, s88
	s_add_u32 s8, s86, s4
	s_waitcnt lgkmcnt(0)
	s_mov_b32 s1, s12
	v_mov_b32_e32 v78, v76
	s_mov_b32 s13, s12
	s_addc_u32 s9, s87, s5
	s_abs_i32 s22, s13
	v_cvt_f32_u32_e32 v2, s22
	v_lshlrev_b32_e32 v0, 2, v78
	v_and_b32_e32 v84, 60, v0
	s_sub_i32 s2, 0, s22
	v_rcp_iflag_f32_e32 v0, v2
	s_mov_b32 s14, s88
	s_add_i32 s15, s14, s13
	v_mul_f32_e32 v0, 0x4f7ffffe, v0
	v_cvt_u32_f32_e32 v0, v0
	s_abs_i32 s1, s15
	s_ashr_i32 s0, s15, 31
	v_ashrrev_i32_e32 v80, 3, v78
	v_readfirstlane_b32 s23, v0
	s_mul_i32 s2, s2, s23
	s_mul_hi_u32 s2, s23, s2
	s_add_i32 s23, s23, s2
	s_mul_hi_u32 s2, s1, s23
	s_mul_i32 s2, s2, s22
	s_sub_i32 s1, s1, s2
	s_sub_i32 s2, s1, s22
	s_cmp_ge_u32 s1, s22
	s_cselect_b32 s1, s2, s1
	s_sub_i32 s2, s1, s22
	s_cmp_ge_u32 s1, s22
	s_cselect_b32 s1, s2, s1
	s_xor_b32 s1, s1, s0
	v_lshlrev_b32_e32 v2, 3, v78
	s_sub_i32 s24, s1, s0
	v_ashrrev_i32_e32 v79, 4, v78
	v_mov_b32_e32 v1, 0
	v_lshl_add_u32 v81, v84, 2, 0
	v_and_b32_e32 v82, 56, v2
	s_cmpk_lt_i32 s24, 0x480
	v_lshl_add_u32 v83, v80, 2, 0
	s_load_dword s59, s[90:91], 0xd8
	v_mbcnt_lo_u32_b32 v100, -1, 0
	v_mbcnt_hi_u32_b32 v100, -1, v100
	s_lshr_b32 s69, s94, 6
	s_lshl_b32 s82, s69, 10
	s_lshl_b32 s83, s69, 1
	s_lshr_b32 s98, s69, 2
	v_lshrrev_b32_e32 v101, 5, v100
	v_and_b32_e32 v113, 31, v100
	s_add_i32 s70, s83, 0
	v_add_u32_e32 v102, s70, v101
	s_add_i32 s70, s98, 0
	v_xor_b32_e32 v106, s70, v113
	v_lshlrev_b32_e32 v106, 4, v106
	s_add_i32 s70, s83, 16
	v_add_u32_e32 v103, s70, v101
	s_add_i32 s70, s98, 2
	v_xor_b32_e32 v107, s70, v113
	v_lshlrev_b32_e32 v107, 4, v107
	s_add_i32 s70, s83, 32
	v_add_u32_e32 v104, s70, v101
	s_add_i32 s70, s98, 4
	v_xor_b32_e32 v108, s70, v113
	v_lshlrev_b32_e32 v108, 4, v108
	s_add_i32 s70, s83, 48
	v_add_u32_e32 v105, s70, v101
	s_add_i32 s70, s98, 6
	v_xor_b32_e32 v109, s70, v113
	v_lshlrev_b32_e32 v109, 4, v109
	s_lshr_b32 s70, s94, 3
	v_lshrrev_b32_e32 v112, 3, v100
	v_add_u32_e32 v112, s70, v112
	v_and_b32_e32 v101, 7, v100
	v_lshlrev_b32_e32 v111, 4, v101
	v_lshrrev_b32_e32 v113, 2, v112
	v_xor_b32_e32 v113, v113, v101
	v_lshlrev_b32_e32 v113, 4, v113
	v_lshl_add_u32 v110, v101, 12, v113
	v_and_b32_e32 v113, 3, v112
	v_lshl_add_u32 v110, v113, 2, v110
	s_waitcnt lgkmcnt(0)
	s_add_u32 s61, s88, 3008
	s_mov_b32 s101, 3304
	s_cmp_eq_u32 s59, 256
	s_cbranch_scc1 .Lwp1_gridok
	s_mov_b32 s61, s88
	s_mov_b32 s101, 7520

.LBB0_966:
	s_barrier
	s_cmp_lt_u32 s88, 132
	s_cbranch_scc1 .Lwph12_skip
	s_load_dword s59, s[90:91], 0xd8
	v_mbcnt_lo_u32_b32 v100, -1, 0
	v_mbcnt_hi_u32_b32 v100, -1, v100
	s_lshr_b32 s69, s94, 6
	s_lshl_b32 s82, s69, 10
	s_lshl_b32 s83, s69, 1
	s_lshr_b32 s98, s69, 2
	v_lshrrev_b32_e32 v101, 5, v100
	v_and_b32_e32 v113, 31, v100
	s_add_i32 s70, s83, 0
	v_add_u32_e32 v102, s70, v101
	s_add_i32 s70, s98, 0
	v_xor_b32_e32 v106, s70, v113
	v_lshlrev_b32_e32 v106, 4, v106
	s_add_i32 s70, s83, 16
	v_add_u32_e32 v103, s70, v101
	s_add_i32 s70, s98, 2
	v_xor_b32_e32 v107, s70, v113
	v_lshlrev_b32_e32 v107, 4, v107
	s_add_i32 s70, s83, 32
	v_add_u32_e32 v104, s70, v101
	s_add_i32 s70, s98, 4
	v_xor_b32_e32 v108, s70, v113
	v_lshlrev_b32_e32 v108, 4, v108
	s_add_i32 s70, s83, 48
	v_add_u32_e32 v105, s70, v101
	s_add_i32 s70, s98, 6
	v_xor_b32_e32 v109, s70, v113
	v_lshlrev_b32_e32 v109, 4, v109
	s_lshr_b32 s70, s94, 3
	v_lshrrev_b32_e32 v112, 3, v100
	v_add_u32_e32 v112, s70, v112
	v_and_b32_e32 v101, 7, v100
	v_lshlrev_b32_e32 v111, 4, v101
	v_lshrrev_b32_e32 v113, 2, v112
	v_xor_b32_e32 v113, v113, v101
	v_lshlrev_b32_e32 v113, 4, v113
	v_lshl_add_u32 v110, v101, 12, v113
	v_and_b32_e32 v113, 3, v112
	v_lshl_add_u32 v110, v113, 2, v110
	s_waitcnt lgkmcnt(0)
	s_cmp_lg_u32 s59, 256
	s_cbranch_scc1 .Lwph12_end
	s_sub_u32 s61, s88, 132
	s_add_u32 s61, s61, 3304
	s_mov_b32 s59, 124
	s_mov_b32 s101, 7520
	s_mov_b32 s60, s61
	s_mov_b32 s58, -2
